# grid barrier: XCD leader publishes generation flag before its own L1 invalidate (9 sites)
# speedup vs baseline: 1.0002x; 1.0002x over previous
; __device__ __forceinline__ unsigned xb_add(unsigned* p, unsigned v) { return __hip_atomic_fetch_add(p, v, __ATOMIC_RELAXED, __HIP_MEMORY_SCOPE_AGENT); }
; __device__ __forceinline__ void xcd_barrier(const XcdBarrier& b, int tid) {
;     ...
;             __builtin_amdgcn_fence(__ATOMIC_ACQUIRE, "agent");
;             xb_add(&bar[XB_XGEN(b.x)], 1u);
;             asm volatile("s_waitcnt vmcnt(0)" ::: "memory");
.LBB0_207:
	s_or_b64 exec, exec, s[2:3]
	v_readlane_b32 s2, v254, 9
	v_readlane_b32 s3, v254, 10
	s_nop 4
	global_atomic_add v161, v239, s[2:3]
	s_waitcnt vmcnt(0)
	buffer_inv sc1
	s_waitcnt vmcnt(0)
